# attention tile loops: cross-half running-max exchange via v_permlane32_swap instead of ds_bpermute + lgkmcnt(0) (5 of 7 loops)
# baseline (speedup 1.0000x reference)
; DI float fexp2(float x) { return __builtin_amdgcn_exp2f(x); }
; DI float max3f(float a, float b, float c) { float r; asm("v_max3_f32 %0, %1, %2, %3" : "=v"(r) : "v"(a), "v"(b), "v"(c)); return r; }
; DI float max2f(float a, float b) { float r; asm("v_max_f32_e32 %0, %1, %2" : "=v"(r) : "v"(a), "v"(b)); return r; }
;     ...
;             float mxa = max3f(s0[0], s1[0], s0[1]), mxb = max3f(s1[1], s0[2], s1[2]);
; #pragma unroll
;             for (int i = 3; i < 15; i += 2) { mxa = max3f(mxa, s0[i], s1[i]); mxb = max3f(mxb, s0[i + 1], s1[i + 1]); }
;             float mx = max3f(mxa, mxb, max2f(s0[15], s1[15]));
;             mx = max2f(mx, __shfl_xor(mx, 32));
;             if (__builtin_amdgcn_ballot_w64(mx - m > 8.0f) != 0ull) {
;                 const float mn = fmaxf(m, mx), mu_ = (mn == -INFINITY) ? 0.f : mn;
;                 const float alpha = fexp2(m - mu_); m = mn; l *= alpha;
; #pragma unroll
;                 for (int i = 0; i < 16; ++i) { o0[i] *= alpha; o1[i] *= alpha; }
;             }
.LBB0_135:
	v_max3_f32 v128, v66, v82, v67
	v_max3_f32 v129, v83, v68, v84
	v_max_f32_e32 v146, v81, v97
	s_mov_b32 s8, 0x41000000
	v_max3_f32 v128, v128, v69, v85
	v_max3_f32 v129, v129, v70, v86
	s_nop 0
	v_max3_f32 v128, v128, v71, v87
	v_max3_f32 v129, v129, v72, v88
	s_nop 0
	v_max3_f32 v128, v128, v73, v89
	v_max3_f32 v129, v129, v74, v90
	s_nop 0
	v_max3_f32 v128, v128, v75, v91
	v_max3_f32 v129, v129, v76, v92
	s_nop 0
	v_max3_f32 v128, v128, v77, v93
	v_max3_f32 v129, v129, v78, v94
	s_nop 0
	v_max3_f32 v128, v128, v79, v95
	v_max3_f32 v129, v129, v80, v96
	s_nop 0
	v_max3_f32 v128, v128, v129, v146
	v_mov_b32_e32 v129, v128
	s_nop 1
	v_permlane32_swap_b32_e32 v129, v128
	v_max_f32_e32 v128, v128, v129
	s_nop 0
	v_sub_f32_e32 v129, v128, v127
	v_cmp_lt_f32_e32 vcc, s8, v129
	s_cbranch_vccz .LBB0_137
	v_max_f32_e32 v128, v128, v128
	v_max_f32_e32 v129, v127, v127
	v_max_f32_e32 v129, v129, v128
	v_cmp_neq_f32_e32 vcc, s79, v129
	s_nop 1
	v_cndmask_b32_e32 v128, 0, v129, vcc
	v_sub_f32_e32 v127, v127, v128
	v_exp_f32_e32 v128, v127
	v_mov_b32_e32 v127, v129
	v_mul_f32_e32 v201, v201, v128
	v_pk_mul_f32 v[48:49], v[48:49], v[128:129] op_sel_hi:[1,0]
	v_pk_mul_f32 v[46:47], v[46:47], v[128:129] op_sel_hi:[1,0]
	v_pk_mul_f32 v[44:45], v[44:45], v[128:129] op_sel_hi:[1,0]
	v_pk_mul_f32 v[42:43], v[42:43], v[128:129] op_sel_hi:[1,0]
	v_pk_mul_f32 v[40:41], v[40:41], v[128:129] op_sel_hi:[1,0]
	v_pk_mul_f32 v[38:39], v[38:39], v[128:129] op_sel_hi:[1,0]
	v_pk_mul_f32 v[36:37], v[36:37], v[128:129] op_sel_hi:[1,0]
	v_pk_mul_f32 v[34:35], v[34:35], v[128:129] op_sel_hi:[1,0]
	v_pk_mul_f32 v[64:65], v[64:65], v[128:129] op_sel_hi:[1,0]
	v_pk_mul_f32 v[62:63], v[62:63], v[128:129] op_sel_hi:[1,0]
	v_pk_mul_f32 v[60:61], v[60:61], v[128:129] op_sel_hi:[1,0]
	v_pk_mul_f32 v[58:59], v[58:59], v[128:129] op_sel_hi:[1,0]
	v_pk_mul_f32 v[56:57], v[56:57], v[128:129] op_sel_hi:[1,0]
	v_pk_mul_f32 v[54:55], v[54:55], v[128:129] op_sel_hi:[1,0]
	v_pk_mul_f32 v[52:53], v[52:53], v[128:129] op_sel_hi:[1,0]
	v_pk_mul_f32 v[50:51], v[50:51], v[128:129] op_sel_hi:[1,0]

; DI float fexp2(float x) { return __builtin_amdgcn_exp2f(x); }
; DI float max3f(float a, float b, float c) { float r; asm("v_max3_f32 %0, %1, %2, %3" : "=v"(r) : "v"(a), "v"(b), "v"(c)); return r; }
; DI float max2f(float a, float b) { float r; asm("v_max_f32_e32 %0, %1, %2" : "=v"(r) : "v"(a), "v"(b)); return r; }
;     ...
;             float mxa = max3f(s0[0], s1[0], s0[1]), mxb = max3f(s1[1], s0[2], s1[2]);
; #pragma unroll
;             for (int i = 3; i < 15; i += 2) { mxa = max3f(mxa, s0[i], s1[i]); mxb = max3f(mxb, s0[i + 1], s1[i + 1]); }
;             float mx = max3f(mxa, mxb, max2f(s0[15], s1[15]));
;             mx = max2f(mx, __shfl_xor(mx, 32));
;             if (__builtin_amdgcn_ballot_w64(mx - m > 8.0f) != 0ull) {
;                 const float mn = fmaxf(m, mx), mu_ = (mn == -INFINITY) ? 0.f : mn;
;                 const float alpha = fexp2(m - mu_); m = mn; l *= alpha;
; #pragma unroll
;                 for (int i = 0; i < 16; ++i) { o0[i] *= alpha; o1[i] *= alpha; }
;             }
.LBB0_194:
	v_max3_f32 v116, v34, v50, v35
	v_max3_f32 v117, v51, v36, v52
	v_max_f32_e32 v118, v49, v65
	s_mov_b32 s0, 0x41000000
	v_max3_f32 v116, v116, v37, v53
	v_max3_f32 v117, v117, v38, v54
	s_nop 0
	v_max3_f32 v116, v116, v39, v55
	v_max3_f32 v117, v117, v40, v56
	s_nop 0
	v_max3_f32 v116, v116, v41, v57
	v_max3_f32 v117, v117, v42, v58
	s_nop 0
	v_max3_f32 v116, v116, v43, v59
	v_max3_f32 v117, v117, v44, v60
	s_nop 0
	v_max3_f32 v116, v116, v45, v61
	v_max3_f32 v117, v117, v46, v62
	s_nop 0
	v_max3_f32 v116, v116, v47, v63
	v_max3_f32 v117, v117, v48, v64
	s_nop 0
	v_max3_f32 v116, v116, v117, v118
	v_mov_b32_e32 v117, v116
	s_nop 1
	v_permlane32_swap_b32_e32 v117, v116
	v_max_f32_e32 v116, v116, v117
	s_nop 0
	v_sub_f32_e32 v117, v116, v115
	v_cmp_lt_f32_e32 vcc, s0, v117
	s_cbranch_vccz .LBB0_196
	v_max_f32_e32 v116, v116, v116
	v_max_f32_e32 v117, v115, v115
	v_max_f32_e32 v117, v117, v116
	v_cmp_neq_f32_e32 vcc, s79, v117
	s_nop 1
	v_cndmask_b32_e32 v116, 0, v117, vcc
	v_sub_f32_e32 v115, v115, v116
	v_exp_f32_e32 v116, v115
	v_mov_b32_e32 v115, v117
	v_mul_f32_e32 v113, v113, v116
	v_pk_mul_f32 v[32:33], v[32:33], v[116:117] op_sel_hi:[1,0]
	v_pk_mul_f32 v[30:31], v[30:31], v[116:117] op_sel_hi:[1,0]
	v_pk_mul_f32 v[28:29], v[28:29], v[116:117] op_sel_hi:[1,0]
	v_pk_mul_f32 v[26:27], v[26:27], v[116:117] op_sel_hi:[1,0]
	v_pk_mul_f32 v[24:25], v[24:25], v[116:117] op_sel_hi:[1,0]
	v_pk_mul_f32 v[22:23], v[22:23], v[116:117] op_sel_hi:[1,0]
	v_pk_mul_f32 v[20:21], v[20:21], v[116:117] op_sel_hi:[1,0]
	v_pk_mul_f32 v[18:19], v[18:19], v[116:117] op_sel_hi:[1,0]
	v_pk_mul_f32 v[16:17], v[16:17], v[116:117] op_sel_hi:[1,0]
	v_pk_mul_f32 v[14:15], v[14:15], v[116:117] op_sel_hi:[1,0]
	v_pk_mul_f32 v[12:13], v[12:13], v[116:117] op_sel_hi:[1,0]
	v_pk_mul_f32 v[10:11], v[10:11], v[116:117] op_sel_hi:[1,0]
	v_pk_mul_f32 v[8:9], v[8:9], v[116:117] op_sel_hi:[1,0]
	v_pk_mul_f32 v[6:7], v[6:7], v[116:117] op_sel_hi:[1,0]
	v_pk_mul_f32 v[4:5], v[4:5], v[116:117] op_sel_hi:[1,0]
	v_pk_mul_f32 v[2:3], v[2:3], v[116:117] op_sel_hi:[1,0]

; DI float fexp2(float x) { return __builtin_amdgcn_exp2f(x); }
; DI float max3f(float a, float b, float c) { float r; asm("v_max3_f32 %0, %1, %2, %3" : "=v"(r) : "v"(a), "v"(b), "v"(c)); return r; }
; DI float max2f(float a, float b) { float r; asm("v_max_f32_e32 %0, %1, %2" : "=v"(r) : "v"(a), "v"(b)); return r; }
;     ...
;             float mxa = max3f(s0[0], s1[0], s0[1]), mxb = max3f(s1[1], s0[2], s1[2]);
; #pragma unroll
;             for (int i = 3; i < 15; i += 2) { mxa = max3f(mxa, s0[i], s1[i]); mxb = max3f(mxb, s0[i + 1], s1[i + 1]); }
;             float mx = max3f(mxa, mxb, max2f(s0[15], s1[15]));
;             mx = max2f(mx, __shfl_xor(mx, 32));
;             if (__builtin_amdgcn_ballot_w64(mx - m > 8.0f) != 0ull) {
;                 const float mn = fmaxf(m, mx), mu_ = (mn == -INFINITY) ? 0.f : mn;
;                 const float alpha = fexp2(m - mu_); m = mn; l *= alpha;
; #pragma unroll
;                 for (int i = 0; i < 16; ++i) { o0[i] *= alpha; o1[i] *= alpha; }
;             }
.LBB0_317:
	v_max3_f32 v123, v50, v34, v51
	v_max3_f32 v124, v35, v52, v36
	v_max_f32_e32 v125, v65, v49
	s_mov_b32 s1, 0x41000000
	v_max3_f32 v123, v123, v53, v37
	v_max3_f32 v124, v124, v54, v38
	s_mov_b32 s42, 0x35000
	v_max3_f32 v123, v123, v55, v39
	v_max3_f32 v124, v124, v56, v40
	s_nop 0
	v_max3_f32 v123, v123, v57, v41
	v_max3_f32 v124, v124, v58, v42
	s_nop 0
	v_max3_f32 v123, v123, v59, v43
	v_max3_f32 v124, v124, v60, v44
	s_nop 0
	v_max3_f32 v123, v123, v61, v45
	v_max3_f32 v124, v124, v62, v46
	s_nop 0
	v_max3_f32 v123, v123, v63, v47
	v_max3_f32 v124, v124, v64, v48
	s_nop 0
	v_max3_f32 v123, v123, v124, v125
	v_mov_b32_e32 v124, v123
	s_nop 1
	v_permlane32_swap_b32_e32 v124, v123
	v_max_f32_e32 v123, v123, v124
	s_nop 0
	v_sub_f32_e32 v124, v123, v112
	v_cmp_lt_f32_e32 vcc, s1, v124
	s_cbranch_vccz .LBB0_319
	v_max_f32_e32 v123, v123, v123
	v_max_f32_e32 v124, v112, v112
	v_max_f32_e32 v123, v124, v123
	v_cmp_neq_f32_e32 vcc, s79, v123
	s_nop 1
	v_cndmask_b32_e32 v124, 0, v123, vcc
	v_sub_f32_e32 v112, v112, v124
	v_exp_f32_e32 v112, v112
	s_nop 0
	v_mul_f32_e32 v105, v105, v112
	v_pk_mul_f32 v[32:33], v[32:33], v[112:113] op_sel_hi:[1,0]
	v_pk_mul_f32 v[30:31], v[30:31], v[112:113] op_sel_hi:[1,0]
	v_pk_mul_f32 v[28:29], v[28:29], v[112:113] op_sel_hi:[1,0]
	v_pk_mul_f32 v[26:27], v[26:27], v[112:113] op_sel_hi:[1,0]
	v_pk_mul_f32 v[24:25], v[24:25], v[112:113] op_sel_hi:[1,0]
	v_pk_mul_f32 v[22:23], v[22:23], v[112:113] op_sel_hi:[1,0]
	v_pk_mul_f32 v[20:21], v[20:21], v[112:113] op_sel_hi:[1,0]
	v_pk_mul_f32 v[18:19], v[18:19], v[112:113] op_sel_hi:[1,0]
	v_pk_mul_f32 v[16:17], v[16:17], v[112:113] op_sel_hi:[1,0]
	v_pk_mul_f32 v[14:15], v[14:15], v[112:113] op_sel_hi:[1,0]
	v_pk_mul_f32 v[12:13], v[12:13], v[112:113] op_sel_hi:[1,0]
	v_pk_mul_f32 v[10:11], v[10:11], v[112:113] op_sel_hi:[1,0]
	v_pk_mul_f32 v[8:9], v[8:9], v[112:113] op_sel_hi:[1,0]
	v_pk_mul_f32 v[6:7], v[6:7], v[112:113] op_sel_hi:[1,0]
	v_pk_mul_f32 v[4:5], v[4:5], v[112:113] op_sel_hi:[1,0]
	v_pk_mul_f32 v[2:3], v[2:3], v[112:113] op_sel_hi:[1,0]
	v_mov_b32_e32 v112, v123

; DI float fexp2(float x) { return __builtin_amdgcn_exp2f(x); }
; DI float max3f(float a, float b, float c) { float r; asm("v_max3_f32 %0, %1, %2, %3" : "=v"(r) : "v"(a), "v"(b), "v"(c)); return r; }
; DI float max2f(float a, float b) { float r; asm("v_max_f32_e32 %0, %1, %2" : "=v"(r) : "v"(a), "v"(b)); return r; }
;     ...
;             float mxa = max3f(s0[0], s1[0], s0[1]), mxb = max3f(s1[1], s0[2], s1[2]);
; #pragma unroll
;             for (int i = 3; i < 15; i += 2) { mxa = max3f(mxa, s0[i], s1[i]); mxb = max3f(mxb, s0[i + 1], s1[i + 1]); }
;             float mx = max3f(mxa, mxb, max2f(s0[15], s1[15]));
;             mx = max2f(mx, __shfl_xor(mx, 32));
;             if (__builtin_amdgcn_ballot_w64(mx - m > 8.0f) != 0ull) {
;                 const float mn = fmaxf(m, mx), mu_ = (mn == -INFINITY) ? 0.f : mn;
;                 const float alpha = fexp2(m - mu_); m = mn; l *= alpha;
; #pragma unroll
;                 for (int i = 0; i < 16; ++i) { o0[i] *= alpha; o1[i] *= alpha; }
;             }
.LBB0_331:
	v_max3_f32 v123, v34, v50, v35
	v_max3_f32 v124, v51, v36, v52
	v_max_f32_e32 v125, v49, v65
	s_mov_b32 s0, 0x41000000
	v_max3_f32 v123, v123, v37, v53
	v_max3_f32 v124, v124, v38, v54
	s_nop 0
	v_max3_f32 v123, v123, v39, v55
	v_max3_f32 v124, v124, v40, v56
	s_nop 0
	v_max3_f32 v123, v123, v41, v57
	v_max3_f32 v124, v124, v42, v58
	s_nop 0
	v_max3_f32 v123, v123, v43, v59
	v_max3_f32 v124, v124, v44, v60
	s_nop 0
	v_max3_f32 v123, v123, v45, v61
	v_max3_f32 v124, v124, v46, v62
	s_nop 0
	v_max3_f32 v123, v123, v47, v63
	v_max3_f32 v124, v124, v48, v64
	s_nop 0
	v_max3_f32 v123, v123, v124, v125
	v_mov_b32_e32 v124, v123
	s_nop 1
	v_permlane32_swap_b32_e32 v124, v123
	v_max_f32_e32 v123, v123, v124
	s_nop 0
	v_sub_f32_e32 v124, v123, v112
	v_cmp_lt_f32_e32 vcc, s0, v124
	s_cbranch_vccz .LBB0_333
	v_max_f32_e32 v123, v123, v123
	v_max_f32_e32 v124, v112, v112
	v_max_f32_e32 v123, v124, v123
	v_cmp_neq_f32_e32 vcc, s79, v123
	s_nop 1
	v_cndmask_b32_e32 v124, 0, v123, vcc
	v_sub_f32_e32 v112, v112, v124
	v_exp_f32_e32 v112, v112
	s_nop 0
	v_mul_f32_e32 v105, v105, v112
	v_pk_mul_f32 v[32:33], v[32:33], v[112:113] op_sel_hi:[1,0]
	v_pk_mul_f32 v[30:31], v[30:31], v[112:113] op_sel_hi:[1,0]
	v_pk_mul_f32 v[28:29], v[28:29], v[112:113] op_sel_hi:[1,0]
	v_pk_mul_f32 v[26:27], v[26:27], v[112:113] op_sel_hi:[1,0]
	v_pk_mul_f32 v[24:25], v[24:25], v[112:113] op_sel_hi:[1,0]
	v_pk_mul_f32 v[22:23], v[22:23], v[112:113] op_sel_hi:[1,0]
	v_pk_mul_f32 v[20:21], v[20:21], v[112:113] op_sel_hi:[1,0]
	v_pk_mul_f32 v[18:19], v[18:19], v[112:113] op_sel_hi:[1,0]
	v_pk_mul_f32 v[16:17], v[16:17], v[112:113] op_sel_hi:[1,0]
	v_pk_mul_f32 v[14:15], v[14:15], v[112:113] op_sel_hi:[1,0]
	v_pk_mul_f32 v[12:13], v[12:13], v[112:113] op_sel_hi:[1,0]
	v_pk_mul_f32 v[10:11], v[10:11], v[112:113] op_sel_hi:[1,0]
	v_pk_mul_f32 v[8:9], v[8:9], v[112:113] op_sel_hi:[1,0]
	v_pk_mul_f32 v[6:7], v[6:7], v[112:113] op_sel_hi:[1,0]
	v_pk_mul_f32 v[4:5], v[4:5], v[112:113] op_sel_hi:[1,0]
	v_pk_mul_f32 v[2:3], v[2:3], v[112:113] op_sel_hi:[1,0]
	v_mov_b32_e32 v112, v123
